# GEMM1 tile loop: scalar load for the next-tile byte instead of global_load_ubyte + vmcnt(0) drain (on top of P0 fast path with nt loads)
# speedup vs baseline: 1.0111x; 1.0084x over previous
.LBB0_71:
	s_add_i32 s67, s67, 1
	s_mul_i32 s1, s67, s93
	s_mul_hi_u32 s4, s67, s92
	s_add_i32 s4, s4, s1
	s_mul_i32 s1, s67, s92
	s_add_u32 s38, s1, s2
	s_addc_u32 s39, s4, s3
	v_cmp_ge_i64_e32 vcc, s[38:39], v[180:181]
	v_cmp_lt_i64_e64 s[4:5], s[38:39], v[180:181]
	s_cbranch_vccnz .LBB0_73
	s_ashr_i32 s1, s38, 31
	s_lshr_b32 s1, s1, 29
	s_add_i32 s1, s38, s1
	s_ashr_i32 s9, s1, 3
	s_and_b32 s1, s1, -8
	s_sub_i32 s1, s38, s1
	s_lshr_b32 s16, s1, 31
	s_or_b32 s16, s59, s16
	s_mul_i32 s1, s1, s16
	s_add_i32 s1, s1, s9
	s_abs_i32 s16, s1
	s_mul_hi_u32 s33, s16, s61
	s_mul_i32 s34, s33, s58
	s_ashr_i32 s9, s1, 31
	s_sub_i32 s16, s16, s34
	s_xor_b32 s9, s9, s60
	s_add_i32 s34, s33, 1
	s_sub_i32 s35, s16, s58
	s_cmp_ge_u32 s16, s58
	s_cselect_b32 s33, s34, s33
	s_cselect_b32 s16, s35, s16
	s_add_i32 s34, s33, 1
	s_cmp_ge_u32 s16, s58
	s_cselect_b32 s16, s34, s33
	s_xor_b32 s16, s16, s9
	s_sub_i32 s9, s16, s9
	s_lshl_b32 s16, s9, 1
	s_sub_i32 s33, 64, s16
	s_min_i32 s33, s33, 2
	s_abs_i32 s34, s33
	v_cvt_f32_u32_e32 v0, s34
	s_sub_i32 s36, 0, s34
	s_mul_i32 s9, s9, s57
	s_sub_i32 s1, s1, s9
	v_rcp_iflag_f32_e32 v0, v0
	s_abs_i32 s35, s1
	s_xor_b32 s9, s1, s33
	s_ashr_i32 s9, s9, 31
	v_mul_f32_e32 v0, 0x4f7ffffe, v0
	v_cvt_u32_f32_e32 v0, v0
	s_nop 0
	v_readfirstlane_b32 s37, v0
	s_mul_i32 s36, s36, s37
	s_mul_hi_u32 s36, s37, s36
	s_add_i32 s37, s37, s36
	s_mul_hi_u32 s36, s35, s37
	s_mul_i32 s37, s36, s34
	s_sub_i32 s35, s35, s37
	s_add_i32 s37, s36, 1
	s_sub_i32 s38, s35, s34
	s_cmp_ge_u32 s35, s34
	s_cselect_b32 s36, s37, s36
	s_cselect_b32 s35, s38, s35
	s_add_i32 s37, s36, 1
	s_cmp_ge_u32 s35, s34
	s_cselect_b32 s34, s37, s36
	s_xor_b32 s34, s34, s9
	s_sub_i32 s9, s34, s9
	s_mul_i32 s33, s9, s33
	s_sub_i32 s1, s1, s33
	s_add_i32 s34, s1, s16
	s_and_b32 s1, s9, -4
	s_add_u32 s1, s1, 0x190
	s_load_dword s36, s[70:71], s1
	s_and_b32 s37, s9, 3
	s_lshl_b32 s37, s37, 3
	s_waitcnt lgkmcnt(0)
	s_lshr_b32 s36, s36, s37
	s_and_b32 s36, s36, 0xff
